# prologue RMS loop: next-row software prefetch (HBM-latency-bound first touch of x_prompt)
# speedup vs baseline: 1.0123x; 1.0123x over previous
.LBB0_42:
	v_readlane_b32 s4, v253, 8
	v_readlane_b32 s5, v253, 9
	s_or_b64 exec, exec, s[4:5]
	v_mov_b32_e32 v0, v204
	v_readlane_b32 s3, v253, 6
	v_ashrrev_i32_e32 v1, 6, v0
	s_nop 0
	v_add_u32_e32 v16, s3, v1
	s_mov_b32 s3, 0x8100
	v_cmp_gt_i32_e32 vcc, s3, v16
	s_and_saveexec_b64 s[8:9], vcc
	v_readlane_b32 s84, v253, 2
	s_mov_b64 s[76:77], s[16:17]
	v_readlane_b32 s85, v253, 3
	v_readlane_b32 s50, v253, 4
	s_cbranch_execz .LBB0_47
	v_mbcnt_lo_u32_b32 v1, -1, 0
	v_mbcnt_hi_u32_b32 v1, -1, v1
	v_and_b32_e32 v2, 64, v1
	v_add_u32_e32 v2, 64, v2
	v_xor_b32_e32 v3, 1, v1
	v_cmp_lt_i32_e32 vcc, v3, v2
	s_load_dwordx4 s[4:7], s[76:77], 0x0
	s_load_dwordx2 s[18:19], s[76:77], 0xc8
	v_cndmask_b32_e32 v3, v1, v3, vcc
	v_lshlrev_b32_e32 v26, 2, v3
	v_xor_b32_e32 v3, 2, v1
	v_cmp_lt_i32_e32 vcc, v3, v2
	v_ashrrev_i32_e32 v17, 31, v16
	v_and_b32_e32 v0, 63, v0
	v_cndmask_b32_e32 v3, v1, v3, vcc
	v_lshlrev_b32_e32 v27, 2, v3
	v_xor_b32_e32 v3, 4, v1
	v_cmp_lt_i32_e32 vcc, v3, v2
	s_waitcnt lgkmcnt(0)
	s_cmp_lg_u64 s[18:19], 0
	v_mov_b32_e32 v19, 0
	v_cndmask_b32_e32 v3, v1, v3, vcc
	v_lshlrev_b32_e32 v28, 2, v3
	v_xor_b32_e32 v3, 8, v1
	v_cmp_lt_i32_e32 vcc, v3, v2
	v_lshlrev_b32_e32 v18, 4, v0
	s_cselect_b64 s[16:17], -1, 0
	v_cndmask_b32_e32 v3, v1, v3, vcc
	v_lshlrev_b32_e32 v29, 2, v3
	v_xor_b32_e32 v3, 16, v1
	v_cmp_lt_i32_e32 vcc, v3, v2
	v_lshl_add_u64 v[20:21], s[18:19], 0, v[18:19]
	s_mov_b64 s[18:19], 0x5100000
	v_cndmask_b32_e32 v3, v1, v3, vcc
	v_lshlrev_b32_e32 v30, 2, v3
	v_xor_b32_e32 v3, 32, v1
	v_cmp_lt_i32_e32 vcc, v3, v2
	s_ashr_i32 s15, s14, 31
	s_mov_b64 s[10:11], 0
	v_cndmask_b32_e32 v1, v1, v3, vcc
	v_lshlrev_b64 v[2:3], 11, v[16:17]
	v_lshl_or_b32 v2, v0, 3, v2
	v_lshl_add_u64 v[2:3], s[0:1], 0, v[2:3]
	v_lshlrev_b32_e32 v31, 2, v1
	v_lshl_add_u64 v[22:23], v[2:3], 0, s[18:19]
	s_lshl_b64 s[18:19], s[14:15], 11
	s_mov_b32 s3, 0x8000
	v_mov_b32_e32 v32, s7
	v_mov_b32_e32 v33, s5
	v_mov_b32_e32 v34, s6
	v_mov_b32_e32 v35, s4
	v_lshlrev_b32_e32 v24, 4, v0
	v_mov_b32_e32 v25, v19
	s_movk_i32 s6, 0x7fff
	v_mov_b32_e32 v36, 0x358637bd
	s_mov_b32 s7, 0x800000
	s_mov_b32 s20, 0xffff0000
	s_mov_b32 s21, 0x80ff
	v_mov_b32_e32 v76, v16
	v_cmp_gt_i32_e32 vcc, s3, v76
	v_add_u32_e32 v77, 0xffff8000, v76
	v_cndmask_b32_e32 v79, v32, v33, vcc
	v_cndmask_b32_e32 v78, v34, v35, vcc
	v_cndmask_b32_e32 v77, v77, v76, vcc
	v_lshlrev_b32_e32 v76, 12, v77
	v_or_b32_e32 v76, v76, v24
	v_mov_b32_e32 v77, 0
	v_lshl_add_u64 v[78:79], v[78:79], 0, v[76:77]
	global_load_dwordx4 v[60:63], v[78:79], off
	global_load_dwordx4 v[64:67], v[78:79], off offset:1024
	global_load_dwordx4 v[72:75], v[78:79], off offset:3072
	global_load_dwordx4 v[68:71], v[78:79], off offset:2048
	s_waitcnt vmcnt(0)
	s_branch .LBB0_45

.LBB0_45:
	s_waitcnt vmcnt(4)
	v_mov_b64_e32 v[12:13], v[60:61]
	v_mov_b64_e32 v[14:15], v[62:63]
	v_mov_b64_e32 v[8:9], v[64:65]
	v_mov_b64_e32 v[10:11], v[66:67]
	v_mov_b64_e32 v[0:1], v[72:73]
	v_mov_b64_e32 v[2:3], v[74:75]
	v_mov_b64_e32 v[4:5], v[68:69]
	v_mov_b64_e32 v[6:7], v[70:71]
	v_add_u32_e32 v76, s14, v16
	v_min_i32_e32 v76, s21, v76
	v_cmp_gt_i32_e32 vcc, s3, v76
	v_add_u32_e32 v77, 0xffff8000, v76
	v_cndmask_b32_e32 v79, v32, v33, vcc
	v_cndmask_b32_e32 v78, v34, v35, vcc
	v_cndmask_b32_e32 v77, v77, v76, vcc
	v_lshlrev_b32_e32 v76, 12, v77
	v_or_b32_e32 v76, v76, v24
	v_mov_b32_e32 v77, 0
	v_lshl_add_u64 v[78:79], v[78:79], 0, v[76:77]
	global_load_dwordx4 v[60:63], v[78:79], off
	global_load_dwordx4 v[64:67], v[78:79], off offset:1024
	global_load_dwordx4 v[72:75], v[78:79], off offset:3072
	global_load_dwordx4 v[68:71], v[78:79], off offset:2048
	v_cmp_lt_i32_e32 vcc, s6, v16
	s_and_b64 s[22:23], s[16:17], vcc
	v_pk_mul_f32 v[38:39], v[14:15], v[14:15]
	v_pk_mul_f32 v[40:41], v[12:13], v[12:13]
	v_pk_mul_f32 v[42:43], v[10:11], v[10:11]
	v_pk_mul_f32 v[44:45], v[8:9], v[8:9]
	v_pk_mov_b32 v[48:49], v[40:41], v[38:39] op_sel:[1,0]
	v_mov_b32_e32 v41, v39
	v_pk_mov_b32 v[38:39], v[44:45], v[42:43] op_sel:[1,0]
	v_mov_b32_e32 v45, v43
	v_mul_f32_e32 v18, v5, v5
	v_mul_f32_e32 v46, v7, v7
	v_pk_add_f32 v[40:41], v[48:49], v[40:41]
	v_pk_add_f32 v[38:39], v[38:39], v[44:45]
	v_mul_f32_e32 v37, v0, v0
	v_mul_f32_e32 v50, v1, v1
	v_mul_f32_e32 v51, v2, v2
	v_mul_f32_e32 v52, v3, v3
	v_pk_fma_f32 v[42:43], v[4:5], v[4:5], v[18:19] op_sel_hi:[1,1,0]
	v_pk_fma_f32 v[46:47], v[6:7], v[6:7], v[46:47] op_sel_hi:[1,1,0]
	v_pk_add_f32 v[40:41], v[40:41], v[40:41] op_sel:[0,1] op_sel_hi:[1,0]
	v_pk_add_f32 v[38:39], v[38:39], v[38:39] op_sel:[0,1] op_sel_hi:[1,0]
	v_mov_b32_e32 v43, v51
	v_mov_b32_e32 v47, v52
	v_mov_b32_e32 v41, v37
	v_mov_b32_e32 v39, v50
	v_pk_add_f32 v[38:39], v[40:41], v[38:39]
	v_pk_add_f32 v[40:41], v[42:43], v[46:47]
	s_nop 0
	v_pk_add_f32 v[38:39], v[38:39], v[40:41]
	s_nop 0
	v_add_f32_e32 v18, v38, v39
	ds_bpermute_b32 v37, v26, v18
	s_waitcnt lgkmcnt(0)
	v_add_f32_e32 v18, v18, v37
	ds_bpermute_b32 v37, v27, v18
	s_waitcnt lgkmcnt(0)
	v_add_f32_e32 v18, v18, v37
	ds_bpermute_b32 v37, v28, v18
	s_waitcnt lgkmcnt(0)
	v_add_f32_e32 v18, v18, v37
	ds_bpermute_b32 v37, v29, v18
	s_waitcnt lgkmcnt(0)
	v_add_f32_e32 v18, v18, v37
	ds_bpermute_b32 v37, v30, v18
	s_waitcnt lgkmcnt(0)
	v_add_f32_e32 v37, v18, v37
	ds_bpermute_b32 v38, v31, v37
	s_and_saveexec_b64 s[4:5], s[22:23]
	s_cbranch_execz .LBB0_44
	v_mov_b32_e32 v18, v16
	v_lshlrev_b64 v[40:41], 12, v[18:19]
	v_lshl_add_u64 v[40:41], v[20:21], 0, v[40:41]
	global_store_dwordx4 v[40:41], v[12:15], off
	global_store_dwordx4 v[40:41], v[8:11], off offset:1024
	global_store_dwordx4 v[40:41], v[4:7], off offset:2048
	global_store_dwordx4 v[40:41], v[0:3], off offset:3072
	s_branch .LBB0_44
